# speedup vs baseline: 1.0083x; 1.0043x over previous
; DI unsigned pk_bf16(float lo, float hi) { f32x2_t v = {lo, hi}; return __builtin_bit_cast(unsigned, __builtin_convertvector(v, bf16x2_t)); }
; DI float bflo(unsigned u) { return __uint_as_float(u << 16); }
; DI float bfhi(unsigned u) { return __uint_as_float(u & 0xffff0000u); }
; DI float shfl_xor_l(float v, int mask, int lane) { return __int_as_float(__builtin_amdgcn_ds_bpermute((lane ^ mask) << 2, __float_as_int(v))); }
; DI int crow(int reg, int h) { return (reg & 3) + 8 * (reg >> 2) + 4 * h; }
; DI void attn_task(const Params& p, int hd, int qb) {
;     ...
;     bf16x8 vf[2][2];
; #pragma unroll
;     for (int s2 = 0; s2 < 2; ++s2)
; #pragma unroll
;       for (int dt = 0; dt < 2; ++dt) vf[s2][dt] = *(const bf16x8*)(VT + (size_t)kb * 2048 + dt * 1024 + s2 * 16);
;     bf16x8 kn[4];
;     const int kbn = kb > 0 ? kb - 1 : 0;
; #pragma unroll
;     for (int ks = 0; ks < 4; ++ks) kn[ks] = *(const bf16x8*)(Kbase + (size_t)kbn * 2048 + ks * 512);
;     f32x16 z;
; #pragma unroll
;     for (int e = 0; e < 16; ++e) z[e] = 0.f;
; #pragma unroll
;     for (int ks = 0; ks < 4; ++ks) z = MFMA32(kf[ks], qf[ks], z);
;     const bool diag = (kb == qb);
;     f32x16 lf;
;     float sum = 0.f;
; #pragma unroll
;     for (int e = 0; e < 16; ++e) {
;       const float zz = z[e];
;       float l = -__builtin_amdgcn_logf(1.0f + __builtin_amdgcn_exp2f(zz));
;       l = (zz > 30.f) ? -zz : l;
;       if (diag && crow(e, hh) >= r) l = 0.f;
;       lf[e] = l; sum += l;
;     }
;     sum += shfl_xor_l(sum, 32, lane);
;     f32x16 ee = z;
; #pragma unroll
;     for (int s2 = 0; s2 < 2; ++s2) {
;       u32x4 hi, lo;
; #pragma unroll
;       for (int j = 0; j < 4; ++j) {
;         const float a = lf[8 * s2 + 2 * j], b = lf[8 * s2 + 2 * j + 1];
;         hi[j] = pk_bf16(a, b);
;         lo[j] = pk_bf16(a - bflo(hi[j]), b - bfhi(hi[j]));
;       }
;       ee = MFMA32(tri[s2], __builtin_bit_cast(bf16x8, hi), ee);
;       ee = MFMA32(tri[s2], __builtin_bit_cast(bf16x8, lo), ee);
;     }
;     f32x16 wv;
; #pragma unroll
;     for (int e = 0; e < 16; ++e) {
;       float x = __builtin_amdgcn_exp2f(ee[e] + carry);
;       if (diag && crow(e, hh) >= r) x = 0.f;
;       wv[e] = x;
;     }
; #pragma unroll
;     for (int s2 = 0; s2 < 2; ++s2) {
;       const bf16x8 wp = pack8(wv, s2);
;       o0 = MFMA32(vf[s2][0], wp, o0);
;       o1 = MFMA32(vf[s2][1], wp, o1);
.LBB0_791:
	global_load_dwordx4 v[102:105], v[110:111], off offset:-2048
	global_load_dwordx4 v[98:101], v[110:111], off
	global_load_dwordx4 v[90:93], v[110:111], off offset:-2016
	global_load_dwordx4 v[94:97], v[110:111], off offset:32
	v_add_u32_e32 v64, -1, v108
	v_lshl_add_u64 v[110:111], v[110:111], 0, s[14:15]
	v_lshl_add_u64 v[112:113], v[112:113], 0, s[14:15]
	s_waitcnt vmcnt(7)
	v_mfma_f32_32x32x16_bf16 v[32:47], v[140:143], v[78:81], 0
	s_waitcnt vmcnt(6)
	v_mfma_f32_32x32x16_bf16 v[32:47], v[144:147], v[74:77], v[32:47]
	s_waitcnt vmcnt(5)
	v_mfma_f32_32x32x16_bf16 v[32:47], v[148:151], v[70:73], v[32:47]
	s_waitcnt vmcnt(4)
	v_mfma_f32_32x32x16_bf16 v[32:47], v[152:155], v[66:69], v[32:47]
	global_load_dwordx4 v[140:143], v[112:113], off offset:-2048
	global_load_dwordx4 v[144:147], v[112:113], off offset:-1024
	global_load_dwordx4 v[148:151], v[112:113], off
	global_load_dwordx4 v[152:155], v[112:113], off offset:1024
	s_nop 7
	v_exp_f32_e32 v50, v34
	v_exp_f32_e32 v48, v32
	v_exp_f32_e32 v49, v33
	v_cmp_lt_f32_e32 vcc, s79, v32
	v_add_f32_e32 v50, 1.0, v50
	v_log_f32_e32 v52, v50
	v_exp_f32_e32 v50, v35
	v_add_f32_e32 v48, 1.0, v48
	v_add_f32_e32 v49, 1.0, v49
	v_log_f32_e32 v48, v48
	v_add_f32_e32 v50, 1.0, v50
	v_log_f32_e32 v53, v50
	v_exp_f32_e32 v50, v36
	v_log_f32_e32 v49, v49
	v_cmp_lt_f32_e64 s[38:39], s79, v33
	v_cndmask_b32_e32 v48, v48, v32, vcc
	v_add_f32_e32 v50, 1.0, v50
	v_log_f32_e32 v54, v50
	v_exp_f32_e32 v50, v37
	v_cndmask_b32_e64 v49, v49, v33, s[38:39]
	v_sub_f32_e64 v58, -v48, v49
	v_cmp_lt_f32_e32 vcc, s79, v34
	v_add_f32_e32 v50, 1.0, v50
	v_log_f32_e32 v55, v50
	v_exp_f32_e32 v50, v38
	v_cmp_lt_f32_e64 s[38:39], s79, v35
	v_add_f32_e32 v50, 1.0, v50
	v_log_f32_e32 v56, v50
	v_exp_f32_e32 v50, v39
	s_nop 0
	v_add_f32_e32 v50, 1.0, v50
	v_log_f32_e32 v57, v50
	v_exp_f32_e32 v50, v40
	s_nop 0
	v_add_f32_e32 v50, 1.0, v50
	v_log_f32_e32 v126, v50
	v_exp_f32_e32 v50, v41
	s_nop 0
	v_add_f32_e32 v50, 1.0, v50
	v_log_f32_e32 v127, v50
	v_exp_f32_e32 v50, v42
	s_nop 0
	v_add_f32_e32 v50, 1.0, v50
	v_log_f32_e32 v128, v50
	v_exp_f32_e32 v50, v43
	s_nop 0
	v_add_f32_e32 v50, 1.0, v50
	v_log_f32_e32 v129, v50
	v_exp_f32_e32 v50, v44
	s_nop 0
	v_add_f32_e32 v50, 1.0, v50
	v_log_f32_e32 v130, v50
	v_exp_f32_e32 v50, v45
	s_nop 0
	v_add_f32_e32 v50, 1.0, v50
	v_log_f32_e32 v131, v50
	v_exp_f32_e32 v50, v46
	s_nop 0
	v_add_f32_e32 v50, 1.0, v50
	v_log_f32_e32 v116, v50
	v_exp_f32_e32 v50, v47
	s_nop 0
	v_add_f32_e32 v50, 1.0, v50
	v_log_f32_e32 v117, v50
	v_pk_add_f32 v[50:51], v[48:49], 0 neg_lo:[1,1] neg_hi:[1,1]
	s_nop 0
	v_cvt_pk_bf16_f32 v118, v50, v51
	v_lshlrev_b32_e32 v50, 16, v118
	v_and_b32_e32 v51, 0xffff0000, v118
	v_pk_add_f32 v[48:49], v[48:49], v[50:51] neg_lo:[1,1] neg_hi:[1,1]
	s_nop 0
	v_cvt_pk_bf16_f32 v122, v48, v49
	v_cndmask_b32_e64 v49, v53, v35, s[38:39]
	v_cndmask_b32_e32 v48, v52, v34, vcc
	v_pk_add_f32 v[50:51], v[48:49], 0 neg_lo:[1,1] neg_hi:[1,1]
	v_sub_f32_e32 v52, v58, v48
	v_cvt_pk_bf16_f32 v119, v50, v51
	v_lshlrev_b32_e32 v50, 16, v119
	v_and_b32_e32 v51, 0xffff0000, v119
	v_sub_f32_e32 v52, v52, v49
	v_pk_add_f32 v[48:49], v[48:49], v[50:51] neg_lo:[1,1] neg_hi:[1,1]
	v_cmp_lt_f32_e32 vcc, s79, v36
	v_cmp_lt_f32_e64 s[38:39], s79, v37
	v_cvt_pk_bf16_f32 v123, v48, v49
	v_cndmask_b32_e32 v48, v54, v36, vcc
	v_cndmask_b32_e64 v49, v55, v37, s[38:39]
	v_pk_add_f32 v[50:51], v[48:49], 0 neg_lo:[1,1] neg_hi:[1,1]
	v_sub_f32_e32 v52, v52, v48
	v_cvt_pk_bf16_f32 v120, v50, v51
	v_lshlrev_b32_e32 v50, 16, v120
	v_and_b32_e32 v51, 0xffff0000, v120
	v_sub_f32_e32 v52, v52, v49
	v_pk_add_f32 v[48:49], v[48:49], v[50:51] neg_lo:[1,1] neg_hi:[1,1]
	v_cmp_lt_f32_e32 vcc, s79, v38
	v_cmp_lt_f32_e64 s[38:39], s79, v39
	v_cvt_pk_bf16_f32 v124, v48, v49
	v_cndmask_b32_e32 v48, v56, v38, vcc
	v_cndmask_b32_e64 v49, v57, v39, s[38:39]
	v_pk_add_f32 v[50:51], v[48:49], 0 neg_lo:[1,1] neg_hi:[1,1]
	v_sub_f32_e32 v52, v52, v48
	v_cvt_pk_bf16_f32 v121, v50, v51
	v_lshlrev_b32_e32 v50, 16, v121
	v_and_b32_e32 v51, 0xffff0000, v121
	v_sub_f32_e32 v132, v52, v49
	v_pk_add_f32 v[48:49], v[48:49], v[50:51] neg_lo:[1,1] neg_hi:[1,1]
	v_cmp_lt_f32_e32 vcc, s79, v40
	v_cmp_lt_f32_e64 s[38:39], s79, v41
	v_cvt_pk_bf16_f32 v125, v48, v49
	v_mfma_f32_32x32x16_bf16 v[48:63], v[82:85], v[118:121], v[32:47]
	s_nop 6
	v_cndmask_b32_e64 v33, v127, v41, s[38:39]
	v_cndmask_b32_e32 v32, v126, v40, vcc
	v_add_f32_e64 v34, -v32, neg(0)
	v_add_f32_e64 v35, -v33, neg(0)
	v_sub_f32_e32 v36, v132, v32
	v_sub_f32_e32 v37, v36, v33
	v_cvt_pk_bf16_f32 v36, v34, v35
	v_lshlrev_b32_e32 v34, 16, v36
	v_and_b32_e32 v35, 0xffff0000, v36
	v_cmp_lt_f32_e32 vcc, s79, v42
	v_cmp_lt_f32_e64 s[38:39], s79, v43
	v_pk_add_f32 v[32:33], v[32:33], v[34:35] neg_lo:[1,1] neg_hi:[1,1]
	v_cndmask_b32_e32 v34, v128, v42, vcc
	v_cndmask_b32_e64 v35, v129, v43, s[38:39]
	v_pk_add_f32 v[38:39], v[34:35], 0 neg_lo:[1,1] neg_hi:[1,1]
	v_cvt_pk_bf16_f32 v32, v32, v33
	v_sub_f32_e32 v33, v37, v34
	v_cvt_pk_bf16_f32 v37, v38, v39
	v_lshlrev_b32_e32 v38, 16, v37
	v_and_b32_e32 v39, 0xffff0000, v37
	v_mfma_f32_32x32x16_bf16 v[48:63], v[82:85], v[122:125], v[48:63]
	v_sub_f32_e32 v40, v33, v35
	v_add_f32_e64 v34, -v34, -v38
	v_add_f32_e64 v35, -v35, -v39
	v_cmp_lt_f32_e32 vcc, s79, v44
	v_cmp_lt_f32_e64 s[38:39], s79, v45
	v_cvt_pk_bf16_f32 v33, v34, v35
	v_cndmask_b32_e32 v34, v130, v44, vcc
	v_cndmask_b32_e64 v35, v131, v45, s[38:39]
	v_pk_add_f32 v[38:39], v[34:35], 0 neg_lo:[1,1] neg_hi:[1,1]
	v_sub_f32_e32 v40, v40, v34
	v_cvt_pk_bf16_f32 v38, v38, v39
	v_sub_f32_e32 v44, v40, v35
	v_lshlrev_b32_e32 v40, 16, v38
	v_and_b32_e32 v41, 0xffff0000, v38
	v_cmp_lt_f32_e32 vcc, s79, v46
	v_cmp_lt_f32_e64 s[38:39], s79, v47
	v_pk_add_f32 v[34:35], v[34:35], v[40:41] neg_lo:[1,1] neg_hi:[1,1]
	v_cndmask_b32_e32 v40, v116, v46, vcc
	v_cndmask_b32_e64 v41, v117, v47, s[38:39]
	v_pk_add_f32 v[42:43], v[40:41], 0 neg_lo:[1,1] neg_hi:[1,1]
	v_cvt_pk_bf16_f32 v34, v34, v35
	v_cvt_pk_bf16_f32 v39, v42, v43
	v_sub_f32_e32 v35, v44, v40
	v_lshlrev_b32_e32 v42, 16, v39
	v_mfma_f32_32x32x16_bf16 v[48:63], v[86:89], v[36:39], v[48:63]
	v_and_b32_e32 v43, 0xffff0000, v39
	v_sub_f32_e32 v44, v35, v41
	v_add_f32_e64 v40, -v40, -v42
	v_add_f32_e64 v41, -v41, -v43
	ds_bpermute_b32 v45, v109, v44
	v_cvt_pk_bf16_f32 v35, v40, v41
	s_nop 1
	v_mfma_f32_32x32x16_bf16 v[48:63], v[86:89], v[32:35], v[48:63]
	s_nop 11
	v_add_f32_e32 v32, v115, v48
	v_add_f32_e32 v33, v115, v49
	v_add_f32_e32 v34, v115, v50
	v_add_f32_e32 v35, v115, v51
	v_add_f32_e32 v36, v115, v52
	v_add_f32_e32 v37, v115, v53
	v_add_f32_e32 v38, v115, v54
	v_add_f32_e32 v39, v115, v55
	v_exp_f32_e32 v32, v32
	v_exp_f32_e32 v33, v33
	v_exp_f32_e32 v34, v34
	v_exp_f32_e32 v35, v35
	v_exp_f32_e32 v36, v36
	v_exp_f32_e32 v37, v37
	v_exp_f32_e32 v38, v38
	v_exp_f32_e32 v39, v39
	v_cvt_pk_bf16_f32 v32, v32, v33
	v_cvt_pk_bf16_f32 v33, v34, v35
	v_cvt_pk_bf16_f32 v34, v36, v37
	v_cvt_pk_bf16_f32 v35, v38, v39
	v_add_f32_e32 v40, v115, v56
	v_add_f32_e32 v41, v115, v57
	s_waitcnt vmcnt(7)
; #define MFMA32(a, b, c) __builtin_amdgcn_mfma_f32_32x32x16_bf16((a), (b), (c), 0, 0, 0)
; DI void attn_task(const Params& p, int hd, int qb) {
;     ...
; #pragma unroll
;     for (int s2 = 0; s2 < 2; ++s2) {
;       const bf16x8 wp = pack8(wv, s2);
;       o0 = MFMA32(vf[s2][0], wp, o0);
;       o1 = MFMA32(vf[s2][1], wp, o1);
;     }
;     carry += sum;
;     if (__all(carry < -160.f)) break;
; #pragma unroll
;     for (int ks = 0; ks < 4; ++ks) kf[ks] = kn[ks];
;   }
	v_mfma_f32_32x32x16_bf16 v[0:15], v[102:105], v[32:35], v[0:15]
	v_add_f32_e32 v42, v115, v58
	v_add_f32_e32 v43, v115, v59
	v_add_f32_e32 v46, v115, v60
	v_add_f32_e32 v47, v115, v61
	v_add_f32_e32 v48, v115, v62
	v_add_f32_e32 v49, v115, v63
	v_exp_f32_e32 v40, v40
	s_waitcnt vmcnt(6)
	v_mfma_f32_32x32x16_bf16 v[16:31], v[98:101], v[32:35], v[16:31]
	v_exp_f32_e32 v41, v41
	v_exp_f32_e32 v42, v42
	v_exp_f32_e32 v43, v43
	v_exp_f32_e32 v46, v46
	v_exp_f32_e32 v47, v47
	v_exp_f32_e32 v48, v48
	v_exp_f32_e32 v49, v49
	v_cvt_pk_bf16_f32 v32, v40, v41
	v_cvt_pk_bf16_f32 v33, v42, v43
	v_cvt_pk_bf16_f32 v34, v46, v47
	v_cvt_pk_bf16_f32 v35, v48, v49
	s_waitcnt vmcnt(5)
	s_nop 0
	v_mfma_f32_32x32x16_bf16 v[0:15], v[90:93], v[32:35], v[0:15]
	s_waitcnt vmcnt(4)
	v_mfma_f32_32x32x16_bf16 v[16:31], v[94:97], v[32:35], v[16:31]
	s_waitcnt lgkmcnt(0)
	v_add_f32_e32 v32, v44, v45
	v_add_f32_e32 v115, v115, v32
	v_cmp_gt_f32_e32 vcc, s18, v115
	s_cmp_eq_u64 vcc, exec
	s_cselect_b64 s[38:39], -1, 0
	v_cmp_gt_u32_e32 vcc, 2, v108
	s_or_b64 s[38:39], s[38:39], vcc
	s_and_b64 s[38:39], exec, s[38:39]
	s_or_b64 s[42:43], s[38:39], s[42:43]
	v_mov_b32_e32 v108, v64
	s_andn2_b64 exec, exec, s[42:43]
	s_cbranch_execnz .LBB0_791
	s_or_b64 exec, exec, s[42:43]
	s_branch .LBB0_786
